# ADIFF item prologue: chunk 0/1 LDS-DMA issued right after the Q/kmax loads (Q stays first in the queue), one vmcnt(0), later redundant prologue waits removed
# baseline (speedup 1.0000x reference)
; #define LAS __attribute__((address_space(3)))
; __device__ __forceinline__ void diff_attn_phase(const Params& p, LAS unsigned char* lds) {
;     ...
;         const int h = it & 7, qc = (it >> 3) & 31, b = it >> 8;
;         const size_t tokb = (size_t)b * SEQ;
;         const bf16_t* qp = PROJ + h * 128 + 64 * comp; const bf16_t* kp = PROJ + 1024 + h * 128; const bf16_t* vp = PROJ + 2048 + h * 128; const bf16_t* zp = PROJ + 3072 + h * 128;
;         const int iw = qc * 256 + 64 * wq;
;         bf16x8 qf[2][4];
;         int ln0 = lane; asm volatile("" : "+v"(ln0));
; #pragma unroll
;         for (int r = 0; r < 2; ++r) { const bf16_t* qrow = qp + (tokb + iw + 32 * r + (ln0 & 31)) * ld + 8 * (ln0 >> 5);
; #pragma unroll
;             for (int ks = 0; ks < 4; ++ks) qf[r][ks] = *(const bf16x8*)(qrow + 16 * ks); }
;         f32x16 O[2][4];
; #pragma unroll
;         for (int r = 0; r < 2; ++r)
; #pragma unroll
;             for (int t = 0; t < 4; ++t)
; #pragma unroll
;                 for (int i = 0; i < 16; ++i) O[r][t][i] = 0.f;
;         float m[2], l[2] = {0.f, 0.f};
;         { const float kmx = __uint_as_float(((const unsigned*)(p.ws + WS_KMAX))[b * 16 + h * 2 + comp]);
; #pragma unroll
;           for (int r = 0; r < 2; ++r) { float s = 0.f;
; #pragma unroll
;               for (int ks = 0; ks < 4; ++ks) { const u32x4 qv = __builtin_bit_cast(u32x4, qf[r][ks]);
; #pragma unroll
;                   for (int i = 0; i < 4; ++i) { const float x0 = bf_lo(qv[i]), x1 = bf_hi(qv[i]); s += x0 * x0 + x1 * x1; } }
;               m[r] = sqrtf(xsum32(s) * kmx) * 1.001f + 1e-3f; } }
;         bf16x8 kone, qm[2];
;         { const unsigned one = hh == 0 ? 0x3F80u : 0u; kone = __builtin_bit_cast(bf16x8, (u32x4){one, 0u, 0u, 0u});
; #pragma unroll
;           for (int r = 0; r < 2; ++r) { const unsigned mb = hh == 0 ? (pk_bf16(-m[r], 0.f) & 0xffffu) : 0u; qm[r] = __builtin_bit_cast(bf16x8, (u32x4){mb, 0u, 0u, 0u}); } }
;         auto issue = [&](int ch, int stg) {
;             const char* kg = (const char*)(kp + (tokb + 64 * ch) * ld); const char* vg = (const char*)(vp + (tokb + 64 * ch) * ld);
;             LAS unsigned char* sb = lds + stg * STG;
; #pragma unroll
;             for (int i = 0; i < 2; ++i) { unsigned o = doff[i]; asm volatile("" : "+v"(o));
;                 __builtin_amdgcn_global_load_lds((const void*)(kg + o), (LAS void*)(sb + dlds[i]), 16, 0, 0);
.LBB0_38:
	s_ashr_i32 s46, s57, 8
	s_and_b32 s5, s57, 7
	s_ashr_i32 s47, s46, 31
	s_lshl_b64 s[26:27], s[46:47], 13
	s_lshl_b32 s2, s5, 8
	s_add_u32 s10, s21, s2
	s_addc_u32 s11, s54, 0
	s_lshl_b32 s2, s57, 5
	s_and_b32 s2, s2, 0x1f00
	v_mov_b32_e32 v1, v240
	s_or_b32 s4, s2, s55
	v_mov_b32_e32 v5, s27
	v_and_or_b32 v4, v1, 31, s4
	v_ashrrev_i32_e32 v1, 2, v1
	v_and_b32_e32 v2, -8, v1
	v_ashrrev_i32_e32 v3, 31, v2
	v_or_b32_e32 v4, s26, v4
	v_lshl_add_u64 v[2:3], v[2:3], 1, s[10:11]
	v_lshlrev_b64 v[6:7], 13, v[4:5]
	v_lshl_add_u64 v[6:7], v[2:3], 0, v[6:7]
	global_load_dwordx4 v[166:169], v[6:7], off
	global_load_dwordx4 v[170:173], v[6:7], off offset:32
	global_load_dwordx4 v[174:177], v[6:7], off offset:64
	global_load_dwordx4 v[178:181], v[6:7], off offset:96
	v_or_b32_e32 v4, 32, v4
	v_lshlrev_b64 v[4:5], 13, v[4:5]
	v_lshl_add_u64 v[2:3], v[2:3], 0, v[4:5]
	global_load_dwordx4 v[182:185], v[2:3], off
	global_load_dwordx4 v[186:189], v[2:3], off offset:32
	global_load_dwordx4 v[190:193], v[2:3], off offset:64
	global_load_dwordx4 v[194:197], v[2:3], off offset:96
	s_lshl_b32 s10, s5, 1
	s_lshl_b32 s2, s46, 4
	s_add_i32 s10, s10, s15
	s_add_i32 s10, s10, s2
	s_ashr_i32 s11, s10, 31
	s_lshl_b64 s[10:11], s[10:11], 2
	s_add_u32 s42, s12, s10
	s_addc_u32 s43, s13, s11
	v_mov_b32_e32 v198, 0
	global_load_dword v1, v198, s[42:43]
	s_lshl_b32 s35, s5, 8
	s_add_u32 s22, s36, s35
	s_addc_u32 s23, s70, 0
	s_add_u32 s25, s78, s35
	s_addc_u32 s28, s83, 0
	s_lshl_b64 s[10:11], s[46:47], 26
	s_add_u32 s42, s25, s10
	s_addc_u32 s43, s28, s11
	s_add_u32 s52, s22, s10
	s_addc_u32 s53, s23, s11
	v_readfirstlane_b32 s2, v242
	s_mov_b32 m0, s2
	s_nop 0
	global_load_lds_dwordx4 v241, s[42:43]
	s_add_i32 s35, s2, 0x4000
	s_mov_b32 m0, s35
	s_nop 0
	global_load_lds_dwordx4 v241, s[52:53]
	v_readfirstlane_b32 s2, v244
	s_mov_b32 m0, s2
	s_nop 0
	global_load_lds_dwordx4 v243, s[42:43]
	s_add_i32 s35, s2, 0x4000
	s_mov_b32 m0, s35
	s_nop 0
	global_load_lds_dwordx4 v243, s[52:53]
	s_or_b32 s35, s10, 0x80000
	s_add_u32 s42, s25, s35
	s_addc_u32 s43, s28, s11
	s_add_u32 s10, s22, s35
	s_addc_u32 s11, s23, s11
	v_readfirstlane_b32 s2, v242
	s_add_i32 s35, s2, 0x8000
	s_mov_b32 m0, s35
	s_nop 0
	global_load_lds_dwordx4 v241, s[42:43]
	s_add_i32 s35, s2, 0xc000
	s_mov_b32 m0, s35
	s_nop 0
	global_load_lds_dwordx4 v241, s[10:11]
	v_readfirstlane_b32 s2, v244
	s_add_i32 s35, s2, 0x8000
	s_mov_b32 m0, s35
	s_nop 0
	global_load_lds_dwordx4 v243, s[42:43]
	s_add_i32 s35, s2, 0xc000
	s_mov_b32 m0, s35
	s_nop 0
	global_load_lds_dwordx4 v243, s[10:11]
	s_waitcnt vmcnt(0)
	v_and_b32_e32 v3, 0xffff0000, v166
	v_lshlrev_b32_e32 v2, 16, v166
	v_mul_f32_e32 v3, v3, v3
	v_and_b32_e32 v4, 0xffff0000, v167
	v_fmac_f32_e32 v3, v2, v2
	v_lshlrev_b32_e32 v2, 16, v167
	v_mul_f32_e32 v4, v4, v4
	v_fmac_f32_e32 v4, v2, v2
	v_add_f32_e32 v2, v3, v4
	v_and_b32_e32 v4, 0xffff0000, v168
	v_lshlrev_b32_e32 v3, 16, v168
	v_mul_f32_e32 v4, v4, v4
	v_fmac_f32_e32 v4, v3, v3
	v_add_f32_e32 v2, v4, v2
	v_and_b32_e32 v4, 0xffff0000, v169
	v_lshlrev_b32_e32 v3, 16, v169
	v_mul_f32_e32 v4, v4, v4
	v_fmac_f32_e32 v4, v3, v3
	v_add_f32_e32 v2, v4, v2
	v_and_b32_e32 v4, 0xffff0000, v170
	v_lshlrev_b32_e32 v3, 16, v170
	v_mul_f32_e32 v4, v4, v4
	v_fmac_f32_e32 v4, v3, v3
	v_add_f32_e32 v2, v4, v2
	v_and_b32_e32 v4, 0xffff0000, v171
	v_lshlrev_b32_e32 v3, 16, v171
	v_mul_f32_e32 v4, v4, v4
	v_fmac_f32_e32 v4, v3, v3
	v_add_f32_e32 v2, v4, v2
	v_and_b32_e32 v4, 0xffff0000, v172
	v_lshlrev_b32_e32 v3, 16, v172
	v_mul_f32_e32 v4, v4, v4
	v_fmac_f32_e32 v4, v3, v3
	v_add_f32_e32 v2, v4, v2
	v_and_b32_e32 v4, 0xffff0000, v173
	v_lshlrev_b32_e32 v3, 16, v173
	v_mul_f32_e32 v4, v4, v4
	v_fmac_f32_e32 v4, v3, v3
	v_add_f32_e32 v2, v4, v2
	v_and_b32_e32 v4, 0xffff0000, v174
	v_lshlrev_b32_e32 v3, 16, v174
	v_mul_f32_e32 v4, v4, v4
	v_fmac_f32_e32 v4, v3, v3
	v_add_f32_e32 v2, v4, v2
	v_and_b32_e32 v4, 0xffff0000, v175
	v_lshlrev_b32_e32 v3, 16, v175
	v_mul_f32_e32 v4, v4, v4
	v_fmac_f32_e32 v4, v3, v3
	v_add_f32_e32 v2, v4, v2
	v_and_b32_e32 v4, 0xffff0000, v176
	v_lshlrev_b32_e32 v3, 16, v176
	v_mul_f32_e32 v4, v4, v4
	v_fmac_f32_e32 v4, v3, v3
	v_add_f32_e32 v2, v4, v2
	v_and_b32_e32 v4, 0xffff0000, v177
	v_lshlrev_b32_e32 v3, 16, v177
	v_mul_f32_e32 v4, v4, v4
	v_fmac_f32_e32 v4, v3, v3
	v_add_f32_e32 v2, v4, v2
	v_and_b32_e32 v4, 0xffff0000, v178
	v_lshlrev_b32_e32 v3, 16, v178
	v_mul_f32_e32 v4, v4, v4
	v_fmac_f32_e32 v4, v3, v3
	v_add_f32_e32 v2, v4, v2
	v_and_b32_e32 v4, 0xffff0000, v179
	v_lshlrev_b32_e32 v3, 16, v179
	v_mul_f32_e32 v4, v4, v4
	v_fmac_f32_e32 v4, v3, v3
	v_add_f32_e32 v2, v4, v2
	v_and_b32_e32 v4, 0xffff0000, v180
	v_lshlrev_b32_e32 v3, 16, v180
	v_mul_f32_e32 v4, v4, v4
	v_fmac_f32_e32 v4, v3, v3
	v_add_f32_e32 v2, v4, v2
	v_and_b32_e32 v4, 0xffff0000, v181
	v_lshlrev_b32_e32 v3, 16, v181
	v_mul_f32_e32 v4, v4, v4
	v_fmac_f32_e32 v4, v3, v3
	v_and_b32_e32 v3, 0xffff0000, v182
	v_add_f32_e32 v4, v4, v2
	v_lshlrev_b32_e32 v2, 16, v182
	v_mul_f32_e32 v3, v3, v3
	v_and_b32_e32 v6, 0xffff0000, v183
	v_fmac_f32_e32 v3, v2, v2
	v_lshlrev_b32_e32 v2, 16, v183
	v_mul_f32_e32 v6, v6, v6
	v_fmac_f32_e32 v6, v2, v2
	v_add_f32_e32 v2, v3, v6
	v_and_b32_e32 v6, 0xffff0000, v184
	v_lshlrev_b32_e32 v3, 16, v184
	v_mul_f32_e32 v6, v6, v6
	v_fmac_f32_e32 v6, v3, v3
	v_add_f32_e32 v2, v6, v2
	v_and_b32_e32 v6, 0xffff0000, v185
	v_lshlrev_b32_e32 v3, 16, v185
	v_mul_f32_e32 v6, v6, v6
	v_fmac_f32_e32 v6, v3, v3
	v_add_f32_e32 v2, v6, v2
	v_and_b32_e32 v6, 0xffff0000, v186
	v_lshlrev_b32_e32 v3, 16, v186
	v_mul_f32_e32 v6, v6, v6
	v_fmac_f32_e32 v6, v3, v3
	v_add_f32_e32 v2, v6, v2
	v_and_b32_e32 v6, 0xffff0000, v187
; #define LAS __attribute__((address_space(3)))
; __device__ __forceinline__ unsigned pk_bf16(float lo, float hi) { const f32x2 v = {lo, hi}; const bf16v2 b = __builtin_convertvector(v, bf16v2); return __builtin_bit_cast(unsigned, b); }
; __device__ __forceinline__ float bf_lo(unsigned u) { return __uint_as_float(u << 16); }
; __device__ __forceinline__ float bf_hi(unsigned u) { return __uint_as_float(u & 0xffff0000u); }
; __device__ __forceinline__ float xsum32(float v) { const auto r = __builtin_amdgcn_permlane32_swap(__float_as_uint(v), __float_as_uint(v), false, false); return __uint_as_float(r[0]) + __uint_as_float(r[1]); }
; __device__ __forceinline__ void diff_attn_phase(const Params& p, LAS unsigned char* lds) {
;     ...
;           for (int r = 0; r < 2; ++r) { float s = 0.f;
; #pragma unroll
;               for (int ks = 0; ks < 4; ++ks) { const u32x4 qv = __builtin_bit_cast(u32x4, qf[r][ks]);
; #pragma unroll
;                   for (int i = 0; i < 4; ++i) { const float x0 = bf_lo(qv[i]), x1 = bf_hi(qv[i]); s += x0 * x0 + x1 * x1; } }
;               m[r] = sqrtf(xsum32(s) * kmx) * 1.001f + 1e-3f; } }
;         bf16x8 kone, qm[2];
;         { const unsigned one = hh == 0 ? 0x3F80u : 0u; kone = __builtin_bit_cast(bf16x8, (u32x4){one, 0u, 0u, 0u});
; #pragma unroll
;           for (int r = 0; r < 2; ++r) { const unsigned mb = hh == 0 ? (pk_bf16(-m[r], 0.f) & 0xffffu) : 0u; qm[r] = __builtin_bit_cast(bf16x8, (u32x4){mb, 0u, 0u, 0u}); } }
;         auto issue = [&](int ch, int stg) {
;             const char* kg = (const char*)(kp + (tokb + 64 * ch) * ld); const char* vg = (const char*)(vp + (tokb + 64 * ch) * ld);
;             LAS unsigned char* sb = lds + stg * STG;
; #pragma unroll
;             for (int i = 0; i < 2; ++i) { unsigned o = doff[i]; asm volatile("" : "+v"(o));
;                 __builtin_amdgcn_global_load_lds((const void*)(kg + o), (LAS void*)(sb + dlds[i]), 16, 0, 0);
;                 __builtin_amdgcn_global_load_lds((const void*)(vg + o), (LAS void*)(sb + 16384 + dlds[i]), 16, 0, 0); }
;         };
;         issue(0, 0); issue(1, 1);
	v_lshlrev_b32_e32 v3, 16, v187
	v_mul_f32_e32 v6, v6, v6
	v_fmac_f32_e32 v6, v3, v3
	v_add_f32_e32 v2, v6, v2
	v_and_b32_e32 v6, 0xffff0000, v188
	v_lshlrev_b32_e32 v3, 16, v188
	v_mul_f32_e32 v6, v6, v6
	v_fmac_f32_e32 v6, v3, v3
	v_add_f32_e32 v2, v6, v2
	v_and_b32_e32 v6, 0xffff0000, v189
	v_lshlrev_b32_e32 v3, 16, v189
	v_mul_f32_e32 v6, v6, v6
	v_fmac_f32_e32 v6, v3, v3
	v_add_f32_e32 v2, v6, v2
	v_and_b32_e32 v6, 0xffff0000, v190
	v_lshlrev_b32_e32 v3, 16, v190
	v_mul_f32_e32 v6, v6, v6
	v_fmac_f32_e32 v6, v3, v3
	v_add_f32_e32 v2, v6, v2
	v_and_b32_e32 v6, 0xffff0000, v191
	v_lshlrev_b32_e32 v3, 16, v191
	v_mul_f32_e32 v6, v6, v6
	v_fmac_f32_e32 v6, v3, v3
	v_add_f32_e32 v2, v6, v2
	v_and_b32_e32 v6, 0xffff0000, v192
	v_lshlrev_b32_e32 v3, 16, v192
	v_mul_f32_e32 v6, v6, v6
	v_fmac_f32_e32 v6, v3, v3
	v_add_f32_e32 v2, v6, v2
	v_and_b32_e32 v6, 0xffff0000, v193
	v_lshlrev_b32_e32 v3, 16, v193
	v_mul_f32_e32 v6, v6, v6
	v_fmac_f32_e32 v6, v3, v3
	v_add_f32_e32 v2, v6, v2
	v_and_b32_e32 v6, 0xffff0000, v194
	v_lshlrev_b32_e32 v3, 16, v194
	v_mul_f32_e32 v6, v6, v6
	v_fmac_f32_e32 v6, v3, v3
	v_add_f32_e32 v2, v6, v2
	v_and_b32_e32 v6, 0xffff0000, v195
	v_lshlrev_b32_e32 v3, 16, v195
	v_mul_f32_e32 v6, v6, v6
	v_fmac_f32_e32 v6, v3, v3
	v_add_f32_e32 v2, v6, v2
	v_and_b32_e32 v6, 0xffff0000, v196
	v_lshlrev_b32_e32 v3, 16, v196
	v_mul_f32_e32 v6, v6, v6
	v_fmac_f32_e32 v6, v3, v3
	v_add_f32_e32 v2, v6, v2
	v_and_b32_e32 v6, 0xffff0000, v197
	v_lshlrev_b32_e32 v3, 16, v197
	v_mul_f32_e32 v6, v6, v6
	v_fmac_f32_e32 v6, v3, v3
	v_add_f32_e32 v2, v6, v2
	v_mov_b32_e32 v5, v4
	v_mov_b32_e32 v3, v2
	s_nop 0
	v_permlane32_swap_b32_e32 v4, v5
	v_permlane32_swap_b32_e32 v2, v3
	s_and_saveexec_b64 s[52:53], s[40:41]
	s_cbranch_execz .LBB0_40
	v_add_f32_e32 v4, v4, v5
	v_mul_f32_e32 v4, v1, v4
	v_mul_f32_e32 v5, 0x4f800000, v4
	v_cmp_gt_f32_e32 vcc, s65, v4
	s_nop 1
	v_cndmask_b32_e32 v4, v4, v5, vcc
	v_sqrt_f32_e32 v5, v4
	s_nop 0
	v_add_u32_e32 v6, -1, v5
	v_fma_f32 v8, -v6, v5, v4
	v_add_u32_e32 v7, 1, v5
	v_cmp_ge_f32_e64 s[42:43], 0, v8
	s_nop 1
	v_cndmask_b32_e64 v6, v5, v6, s[42:43]
	v_fma_f32 v5, -v7, v5, v4
	v_cmp_lt_f32_e64 s[42:43], 0, v5
	s_nop 1
	v_cndmask_b32_e64 v5, v6, v7, s[42:43]
	v_mul_f32_e32 v6, 0x37800000, v5
	v_cndmask_b32_e32 v5, v5, v6, vcc
	v_cmp_class_f32_e32 vcc, v4, v249
	s_nop 1
	v_cndmask_b32_e32 v4, v5, v4, vcc
	v_fmamk_f32 v4, v4, 0x3f8020c5, v252
	v_xor_b32_e32 v4, 0x80000000, v4
	v_cvt_pk_bf16_f32 v4, v4, 0
	v_and_b32_e32 v198, 0xffff, v4
.LBB0_40:
	s_or_b64 exec, exec, s[52:53]
	s_lshl_b32 s2, s5, 7
	s_lshl_b32 s5, s2, 1
	v_add_f32_e32 v2, v2, v3
	v_mul_f32_e32 v1, v1, v2
	v_mul_f32_e32 v2, 0x4f800000, v1
	v_cmp_gt_f32_e32 vcc, s65, v1
	v_mov_b32_e32 v66, v0
	v_mov_b32_e32 v67, v0
	v_cndmask_b32_e32 v1, v1, v2, vcc
	v_sqrt_f32_e32 v2, v1
	v_mov_b32_e32 v80, v0
	v_mov_b32_e32 v81, v0
	v_mov_b32_e32 v68, v0
	v_add_u32_e32 v3, -1, v2
	v_fma_f32 v4, -v3, v2, v1
	v_cmp_ge_f32_e64 s[42:43], 0, v4
	v_add_u32_e32 v4, 1, v2
	v_mov_b32_e32 v69, v0
	v_cndmask_b32_e64 v3, v2, v3, s[42:43]
	v_fma_f32 v2, -v4, v2, v1
	v_cmp_lt_f32_e64 s[42:43], 0, v2
	v_mov_b32_e32 v70, v0
	v_mov_b32_e32 v71, v0
	v_cndmask_b32_e64 v2, v3, v4, s[42:43]
	v_mul_f32_e32 v3, 0x37800000, v2
	v_cndmask_b32_e32 v2, v2, v3, vcc
	v_cmp_class_f32_e32 vcc, v1, v249
	v_mov_b32_e32 v72, v0
	v_mov_b32_e32 v73, v0
	v_cndmask_b32_e32 v1, v2, v1, vcc
	v_fmamk_f32 v1, v1, 0x3f8020c5, v252
	v_xor_b32_e32 v1, 0x80000000, v1
	v_cvt_pk_bf16_f32 v1, v1, 0
	v_and_b32_e32 v1, 0xffff, v1
	v_cndmask_b32_e64 v202, 0, v1, s[40:41]
	v_mov_b32_e32 v1, v0
	v_mov_b32_e32 v74, v0
	v_mov_b32_e32 v75, v0
	v_mov_b32_e32 v76, v0
	v_mov_b32_e32 v77, v0
	v_mov_b32_e32 v78, v0
	v_mov_b32_e32 v79, v0
	v_mov_b64_e32 v[96:97], v[80:81]
	v_mov_b64_e32 v[112:113], v[80:81]
	v_mov_b64_e32 v[128:129], v[80:81]
	v_mov_b64_e32 v[50:51], v[66:67]
	v_mov_b64_e32 v[34:35], v[66:67]
	v_mov_b64_e32 v[18:19], v[66:67]
	v_mov_b64_e32 v[2:3], v[66:67]
	s_mov_b32 s42, 0
	v_mov_b32_e32 v199, v0
	v_mov_b32_e32 v200, v0
	v_mov_b32_e32 v201, v0
	v_mov_b32_e32 v203, v0
	v_mov_b32_e32 v204, v0
	v_mov_b32_e32 v205, v0
	s_mov_b32 s37, 2
	v_mov_b64_e32 v[94:95], v[78:79]
	v_mov_b64_e32 v[92:93], v[76:77]
	v_mov_b64_e32 v[90:91], v[74:75]
	v_mov_b64_e32 v[88:89], v[72:73]
	v_mov_b64_e32 v[86:87], v[70:71]
	v_mov_b64_e32 v[84:85], v[68:69]
	v_mov_b64_e32 v[82:83], v[66:67]
	v_mov_b64_e32 v[110:111], v[78:79]
	v_mov_b64_e32 v[108:109], v[76:77]
	v_mov_b64_e32 v[106:107], v[74:75]
	v_mov_b64_e32 v[104:105], v[72:73]
	v_mov_b64_e32 v[102:103], v[70:71]
	v_mov_b64_e32 v[100:101], v[68:69]
	v_mov_b64_e32 v[98:99], v[66:67]
	v_mov_b64_e32 v[126:127], v[78:79]
	v_mov_b64_e32 v[124:125], v[76:77]
	v_mov_b64_e32 v[122:123], v[74:75]
	v_mov_b64_e32 v[120:121], v[72:73]
	v_mov_b64_e32 v[118:119], v[70:71]
	v_mov_b64_e32 v[116:117], v[68:69]
	v_mov_b64_e32 v[114:115], v[66:67]
	v_mov_b64_e32 v[52:53], v[68:69]
	v_mov_b64_e32 v[54:55], v[70:71]
	v_mov_b64_e32 v[56:57], v[72:73]
	v_mov_b64_e32 v[58:59], v[74:75]
	v_mov_b64_e32 v[60:61], v[76:77]
	v_mov_b64_e32 v[62:63], v[78:79]
	v_mov_b64_e32 v[64:65], v[80:81]
	v_mov_b64_e32 v[36:37], v[68:69]
	v_mov_b64_e32 v[38:39], v[70:71]
	v_mov_b64_e32 v[40:41], v[72:73]
	v_mov_b64_e32 v[42:43], v[74:75]
	v_mov_b64_e32 v[44:45], v[76:77]
	v_mov_b64_e32 v[46:47], v[78:79]
	v_mov_b64_e32 v[48:49], v[80:81]
	v_mov_b64_e32 v[20:21], v[68:69]
	v_mov_b64_e32 v[22:23], v[70:71]
	v_mov_b64_e32 v[24:25], v[72:73]
	v_mov_b64_e32 v[26:27], v[74:75]
	v_mov_b64_e32 v[28:29], v[76:77]
	v_mov_b64_e32 v[30:31], v[78:79]
	v_mov_b64_e32 v[32:33], v[80:81]
	v_mov_b64_e32 v[4:5], v[68:69]
	v_mov_b64_e32 v[6:7], v[70:71]
	v_mov_b64_e32 v[8:9], v[72:73]
	v_mov_b64_e32 v[10:11], v[74:75]
	v_mov_b64_e32 v[12:13], v[76:77]
	v_mov_b64_e32 v[14:15], v[78:79]
	v_mov_b64_e32 v[16:17], v[80:81]
	s_mov_b32 s29, 0
	v_mov_b64_e32 v[212:213], v[0:1]
	v_max_u32_e32 v130, v198, v202
	v_cmp_gt_u32_e32 vcc, 0xc270, v130
	s_nop 3
	s_cmp_eq_u64 vcc, exec
	s_cbranch_scc1 .Lfa_entry
	s_mov_b32 s34, s42
	s_cmpk_eq_i32 s29, 0x7f
	s_mov_b64 s[42:43], -1
	s_cbranch_scc1 .LBB0_43
	s_branch .LBB0_42
